# gate/up GEMM: one barrier per super-phase (leading half keeps post-MFMA barrier, trailing half pre-MFMA barrier, trailing MFMA prio 2), ALIGN_EPI barriers removed
# baseline (speedup 1.0000x reference)
.LBB0_132:
	s_mov_b64 s[12:13], s[88:89]
	v_readlane_b32 s2, v255, 0
	v_readlane_b32 s24, v255, 16
	s_mov_b64 s[0:1], s[94:95]
	v_readlane_b32 s3, v255, 9
	s_add_u32 s0, s12, 0x28600000
	s_addc_u32 s1, s13, 0
	s_sub_i32 s2, s2, s59
	v_mbcnt_lo_u32_b32 v0, -1, 0
	v_mbcnt_hi_u32_b32 v0, -1, v0
	s_mov_b64 s[4:5], -1
	v_lshl_add_u32 v152, s3, 6, v0
	s_ashr_i32 s3, s2, 31
	s_and_b32 s3, s3, s24
	s_add_i32 s25, s3, s2
	v_readlane_b32 s2, v255, 46
	v_readlane_b32 s3, v255, 47
	s_and_b64 vcc, exec, s[2:3]
	s_cbranch_vccz .LBB0_152
	v_mov_b32_e32 v130, v152
	s_cmpk_gt_i32 s25, 0x2bf
	v_readfirstlane_b32 s4, v130
	s_cbranch_scc1 .LBB0_151
	v_mov_b32_e32 v2, v1
	v_mov_b32_e32 v3, v1
	v_mov_b32_e32 v0, v1
	v_mov_b64_e32 v[12:13], v[2:3]
	v_mov_b64_e32 v[10:11], v[0:1]
	s_lshl_b64 s[2:3], s[56:57], 12
	s_add_u32 s48, s0, s2
	v_mfma_f32_16x16x32_bf16 v[118:121], v[10:13], v[10:13], 0
	s_addc_u32 s2, s1, s3
	v_readlane_b32 s3, v255, 45
	v_mfma_f32_16x16x32_bf16 v[110:113], v[10:13], v[10:13], 0
	s_mul_i32 s3, s3, 0x2c00000
	s_add_u32 s3, s12, s3
	v_mfma_f32_16x16x32_bf16 v[102:105], v[10:13], v[10:13], 0
	s_addc_u32 s5, s13, 0
	s_add_u32 s8, s3, 0x200000
	v_mfma_f32_16x16x32_bf16 v[94:97], v[10:13], v[10:13], 0
	s_addc_u32 s3, s5, 0
	s_ashr_i32 s5, s4, 6
	v_mfma_f32_16x16x32_bf16 v[86:89], v[10:13], v[10:13], 0
	s_lshl_b32 s9, s5, 3
	v_bfe_u32 v2, v130, 3, 3
	v_mfma_f32_16x16x32_bf16 v[78:81], v[10:13], v[10:13], 0
	v_or_b32_e32 v4, s9, v2
	v_and_b32_e32 v0, 63, v130
	v_mfma_f32_16x16x32_bf16 v[66:69], v[10:13], v[10:13], 0
	v_lshrrev_b32_e32 v5, 1, v4
	s_lshl_b32 s10, s5, 1
	v_mfma_f32_16x16x32_bf16 v[58:61], v[10:13], v[10:13], 0
	v_bfe_u32 v3, v0, 3, 2
	v_xor_b32_e32 v5, v5, v130
	v_mfma_f32_16x16x32_bf16 v[126:129], v[10:13], v[10:13], 0
	v_lshlrev_b32_e32 v6, 1, v4
	v_and_or_b32 v3, s10, 4, v3
	v_mfma_f32_16x16x32_bf16 v[122:125], v[10:13], v[10:13], 0
	v_lshlrev_b32_e32 v5, 4, v5
	s_and_b32 s10, s9, 0xfffe0
	v_mfma_f32_16x16x32_bf16 v[114:117], v[10:13], v[10:13], 0
	v_and_b32_e32 v6, 24, v6
	s_add_i32 s9, s9, 64
	v_mfma_f32_16x16x32_bf16 v[106:109], v[10:13], v[10:13], 0
	s_and_b32 s49, s2, 0xffff
	s_ashr_i32 s2, s25, 31
	v_and_b32_e32 v5, 0x70, v5
	v_or3_b32 v6, s10, v6, v3
	v_or_b32_e32 v2, s9, v2
	v_mfma_f32_16x16x32_bf16 v[98:101], v[10:13], v[10:13], 0
	s_lshr_b32 s14, s2, 29
	v_lshl_or_b32 v153, v4, 12, v5
	v_lshl_or_b32 v154, v6, 12, v5
	v_lshlrev_b32_e32 v5, 1, v2
	v_mfma_f32_16x16x32_bf16 v[90:93], v[10:13], v[10:13], 0
	s_add_i32 s14, s25, s14
	s_and_b32 s9, s9, 0xfffe0
	v_and_b32_e32 v5, 24, v5
	v_mfma_f32_16x16x32_bf16 v[82:85], v[10:13], v[10:13], 0
	s_ashr_i32 s15, s14, 3
	s_and_b32 s14, s14, -8
	s_ashr_i32 s20, s4, 8
	v_or3_b32 v3, s9, v5, v3
	v_mfma_f32_16x16x32_bf16 v[74:77], v[10:13], v[10:13], 0
	s_and_b32 s9, s3, 0xffff
	s_lshl_b32 s3, s5, 10
	s_sub_i32 s14, s25, s14
	v_mfma_f32_16x16x32_bf16 v[54:57], v[10:13], v[10:13], 0
	s_cmp_lt_i32 s14, 0
	s_movk_i32 s16, 0x59
	v_mfma_f32_16x16x32_bf16 v[46:49], v[10:13], v[10:13], 0
	s_cselect_b32 s16, s16, 0x58
	s_mul_i32 s14, s14, s16
	v_mfma_f32_16x16x32_bf16 v[38:41], v[10:13], v[10:13], 0
	v_lshrrev_b32_e32 v4, 1, v2
	s_add_i32 s14, s14, s15
	v_mfma_f32_16x16x32_bf16 v[30:33], v[10:13], v[10:13], 0
	v_xor_b32_e32 v4, v4, v130
	s_mul_hi_i32 s15, s14, 0x2e8ba2e9
	v_mfma_f32_16x16x32_bf16 v[22:25], v[10:13], v[10:13], 0
	v_lshlrev_b32_e32 v4, 4, v4
	s_lshr_b32 s16, s15, 31
	v_mfma_f32_16x16x32_bf16 v[14:17], v[10:13], v[10:13], 0
	s_ashr_i32 s15, s15, 5
	v_and_b32_e32 v4, 0x70, v4
	v_mfma_f32_16x16x32_bf16 v[6:9], v[10:13], v[10:13], 0
	s_add_i32 s15, s15, s16
	v_lshl_or_b32 v155, v2, 12, v4
	v_lshl_or_b32 v156, v3, 12, v4
	v_mfma_f32_16x16x32_bf16 v[2:5], v[10:13], v[10:13], 0
	s_lshl_b32 s16, s15, 2
	s_mulk_i32 s15, 0xb0
	v_mfma_f32_16x16x32_bf16 v[70:73], v[10:13], v[10:13], 0
	s_sub_i32 s14, s14, s15
	s_bfe_u32 s15, s14, 0x2001d
	v_mfma_f32_16x16x32_bf16 v[62:65], v[10:13], v[10:13], 0
	s_add_i32 s15, s14, s15
	s_sext_i32_i16 s17, s15
	v_mfma_f32_16x16x32_bf16 v[50:53], v[10:13], v[10:13], 0
	s_add_i32 s3, s3, 0
	s_and_b32 s15, s15, 0xfffc
	v_mfma_f32_16x16x32_bf16 v[42:45], v[10:13], v[10:13], 0
	s_ashr_i32 s53, s17, 2
	s_add_i32 s26, s3, 0x10000
	v_mfma_f32_16x16x32_bf16 v[34:37], v[10:13], v[10:13], 0
	s_mov_b32 s10, s50
	s_mov_b32 s11, s51
	s_sub_i32 s14, s14, s15
	v_mfma_f32_16x16x32_bf16 v[26:29], v[10:13], v[10:13], 0
	s_lshl_b32 s60, s53, 20
	s_mov_b32 m0, s26
	s_add_i32 s27, s3, 0x12000
	s_sext_i32_i16 s14, s14
	v_mfma_f32_16x16x32_bf16 v[18:21], v[10:13], v[10:13], 0
	buffer_load_dwordx4 v154, s[8:11], s60 offen lds
	s_mov_b32 m0, s27
	s_add_i32 s28, s3, 0x14000
	s_add_i32 s58, s16, s14
	buffer_load_dwordx4 v156, s[8:11], s60 offen lds
	s_or_b32 s14, s60, 0x80000
	s_mov_b32 m0, s28
	s_add_i32 s29, s3, 0x16000
	buffer_load_dwordx4 v154, s[8:11], s14 offen lds
	s_mov_b32 m0, s29
	s_lshl_b32 s61, s58, 20
	buffer_load_dwordx4 v156, s[8:11], s14 offen lds
	s_mov_b32 m0, s3
	s_add_i32 s30, s3, 0x2000
	buffer_load_dwordx4 v153, s[48:51], s61 offen lds
	s_mov_b32 m0, s30
	s_add_i32 s31, s3, 0x4000
	buffer_load_dwordx4 v155, s[48:51], s61 offen lds
	s_or_b32 s10, s61, 0x80000
	s_mov_b32 m0, s31
	s_add_i32 s34, s3, 0x6000
	buffer_load_dwordx4 v153, s[48:51], s10 offen lds
	s_mov_b32 m0, s34
	v_mfma_f32_16x16x32_bf16 v[10:13], v[10:13], v[10:13], 0
	buffer_load_dwordx4 v155, s[48:51], s10 offen lds
	s_cmp_eq_u32 s20, 1
	s_cselect_b64 s[14:15], -1, 0
	s_cmp_lg_u32 s20, 1
	s_cbranch_scc1 .LBB0_136
.LBB0_136:
	s_mul_i32 s10, s56, 0x2c00
	s_add_u32 s10, s12, s10
	s_addc_u32 s11, s13, 0
	s_add_u32 s16, s10, 0x2a600000
	s_addc_u32 s17, s11, 0
	v_readlane_b32 s10, v255, 51
	v_readlane_b32 s11, v255, 52
	s_lshl_b64 s[10:11], s[10:11], 3
	s_add_u32 s18, s12, s10
	s_addc_u32 s19, s13, s11
	s_lshl_b64 s[10:11], s[56:57], 3
	s_add_u32 s10, s18, s10
	s_addc_u32 s11, s19, s11
	s_add_u32 s18, s10, 0x10000
	s_addc_u32 s19, s11, 0
	s_add_i32 s35, s3, 0x18000
	s_or_b32 s21, s60, 0x80
	s_mov_b32 s10, s50
	s_mov_b32 s11, s51
	s_mov_b32 m0, s35
	s_add_i32 s36, s3, 0x1a000
	s_waitcnt vmcnt(2)
	s_barrier
	buffer_load_dwordx4 v154, s[8:11], s21 offen lds
	s_mov_b32 m0, s36
	s_add_i32 s37, s3, 0x8000
	buffer_load_dwordx4 v156, s[8:11], s21 offen lds
	s_or_b32 s21, s61, 0x80
	s_mov_b32 m0, s37
	s_add_i32 s38, s3, 0xa000
	buffer_load_dwordx4 v153, s[48:51], s21 offen lds
	s_mov_b32 m0, s38
	s_add_i32 s39, s3, 0x1c000
	buffer_load_dwordx4 v155, s[48:51], s21 offen lds
	s_or_b32 s21, s60, 0x80080
	s_mov_b32 m0, s39
	s_add_i32 s40, s3, 0x1e000
	buffer_load_dwordx4 v154, s[8:11], s21 offen lds
	s_mov_b32 m0, s40
	v_and_b32_e32 v131, 15, v130
	buffer_load_dwordx4 v156, s[8:11], s21 offen lds
	v_lshrrev_b32_e32 v0, 4, v0
	v_lshrrev_b32_e32 v130, 1, v130
	v_lshlrev_b32_e32 v132, 7, v131
	v_bitop3_b32 v130, v0, v130, 7 bitop3:0x78
	s_and_b32 s5, s5, 3
	v_lshl_or_b32 v133, s20, 13, v132
	v_lshlrev_b32_e32 v130, 4, v130
	s_waitcnt vmcnt(6)
	s_add_i32 s41, s3, 0xc000
	v_or_b32_e32 v134, v133, v130
	v_bitop3_b32 v133, v133, 64, v130 bitop3:0x36
	v_lshl_or_b32 v132, s5, 12, v132
	s_cmpk_lt_u32 s4, 0x100
	v_lshlrev_b32_e32 v0, 3, v0
	v_or_b32_e32 v157, v132, v130
	v_bitop3_b32 v158, v132, 64, v130 bitop3:0x36
	v_lshl_or_b32 v159, s20, 6, v131
	s_cselect_b64 s[20:21], -1, 0
	v_lshl_or_b32 v160, s5, 5, v0
	s_add_i32 s42, s3, 0xe000
	s_ashr_i32 s43, s24, 31
	s_mov_b32 s44, 0
	v_mov_b64_e32 v[130:131], 0
	v_add_u32_e32 v161, 0, v134
	v_add_u32_e32 v162, 0, v133
	v_mov_b64_e32 v[132:133], 0
	v_mov_b64_e32 v[134:135], 0
	v_mov_b64_e32 v[136:137], 0
	v_mov_b64_e32 v[138:139], 0
	v_mov_b64_e32 v[140:141], 0
	v_mov_b64_e32 v[142:143], 0
	v_mov_b64_e32 v[144:145], 0
	s_barrier
	s_branch .LBB0_139

.LBB0_142:
	s_cmp_eq_u64 s[20:21], 0
	s_cbranch_scc1 .Lg1s_tbody
	s_add_i32 s62, s58, 0xfff80080
	s_and_b64 s[10:11], s[10:11], exec
	s_cselect_b32 s78, s54, s62
	s_cselect_b32 s62, s55, s60
	s_add_i32 s10, 0, 0x10000
	v_add_u32_e32 v0, s10, v157
	v_add_u32_e32 v147, s10, v158
	s_add_i32 s10, 0, 0x14000
	ds_read_b128 v[164:167], v0
	ds_read_b128 v[168:171], v0 offset:2048
	ds_read_b128 v[172:175], v147
	ds_read_b128 v[176:179], v147 offset:2048
	v_add_u32_e32 v0, s10, v157
	v_add_u32_e32 v147, s10, v158
	ds_read_b128 v[180:183], v0
	ds_read_b128 v[184:187], v0 offset:2048
	ds_read_b128 v[188:191], v147
	ds_read_b128 v[192:195], v147 offset:2048
	s_or_b32 s64, s78, 0x80
	s_or_b32 s65, s62, 0x80
	s_mov_b32 m0, s41
	ds_read_b128 v[196:199], v161
	ds_read_b128 v[204:207], v161 offset:2048
	ds_read_b128 v[208:211], v162
	ds_read_b128 v[212:215], v162 offset:2048
	ds_read_b128 v[216:219], v161 offset:4096
	ds_read_b128 v[220:223], v161 offset:6144
	ds_read_b128 v[224:227], v162 offset:4096
	ds_read_b128 v[228:231], v162 offset:6144
	buffer_load_dwordx4 v153, s[48:51], s58 offen lds
	s_mov_b32 m0, s42
	s_nop 0
	buffer_load_dwordx4 v155, s[48:51], s58 offen lds
	s_waitcnt vmcnt(8)
	s_waitcnt lgkmcnt(0)
	s_setprio 1
	s_waitcnt lgkmcnt(0)
	v_mfma_f32_16x16x32_f16 v[118:121], v[164:167], v[196:199], v[118:121]
	v_mfma_f32_16x16x32_f16 v[110:113], v[168:171], v[196:199], v[110:113]
	v_mfma_f32_16x16x32_f16 v[102:105], v[164:167], v[204:207], v[102:105]
	v_mfma_f32_16x16x32_f16 v[94:97], v[168:171], v[204:207], v[94:97]
	v_mfma_f32_16x16x32_f16 v[86:89], v[164:167], v[216:219], v[86:89]
	v_mfma_f32_16x16x32_f16 v[78:81], v[168:171], v[216:219], v[78:81]
	v_mfma_f32_16x16x32_f16 v[66:69], v[164:167], v[220:223], v[66:69]
	v_mfma_f32_16x16x32_f16 v[58:61], v[168:171], v[220:223], v[58:61]
	v_mfma_f32_16x16x32_f16 v[118:121], v[172:175], v[208:211], v[118:121]
	v_mfma_f32_16x16x32_f16 v[110:113], v[176:179], v[208:211], v[110:113]
	v_mfma_f32_16x16x32_f16 v[102:105], v[172:175], v[212:215], v[102:105]
	v_mfma_f32_16x16x32_f16 v[94:97], v[176:179], v[212:215], v[94:97]
	v_mfma_f32_16x16x32_f16 v[86:89], v[172:175], v[224:227], v[86:89]
	v_mfma_f32_16x16x32_f16 v[78:81], v[176:179], v[224:227], v[78:81]
	v_mfma_f32_16x16x32_f16 v[66:69], v[172:175], v[228:231], v[66:69]
	v_mfma_f32_16x16x32_f16 v[58:61], v[176:179], v[228:231], v[58:61]
	s_setprio 0
	s_setprio 1
	v_mfma_f32_16x16x32_f16 v[126:129], v[180:183], v[196:199], v[126:129]
	v_mfma_f32_16x16x32_f16 v[122:125], v[184:187], v[196:199], v[122:125]
	v_mfma_f32_16x16x32_f16 v[114:117], v[180:183], v[204:207], v[114:117]
	v_mfma_f32_16x16x32_f16 v[106:109], v[184:187], v[204:207], v[106:109]
	v_mfma_f32_16x16x32_f16 v[98:101], v[180:183], v[216:219], v[98:101]
	v_mfma_f32_16x16x32_f16 v[90:93], v[184:187], v[216:219], v[90:93]
	v_mfma_f32_16x16x32_f16 v[82:85], v[180:183], v[220:223], v[82:85]
	v_mfma_f32_16x16x32_f16 v[74:77], v[184:187], v[220:223], v[74:77]
	v_mfma_f32_16x16x32_f16 v[126:129], v[188:191], v[208:211], v[126:129]
	v_mfma_f32_16x16x32_f16 v[122:125], v[192:195], v[208:211], v[122:125]
	v_mfma_f32_16x16x32_f16 v[114:117], v[188:191], v[212:215], v[114:117]
	v_mfma_f32_16x16x32_f16 v[106:109], v[192:195], v[212:215], v[106:109]
	v_mfma_f32_16x16x32_f16 v[98:101], v[188:191], v[224:227], v[98:101]
	v_mfma_f32_16x16x32_f16 v[90:93], v[192:195], v[224:227], v[90:93]
	v_mfma_f32_16x16x32_f16 v[82:85], v[188:191], v[228:231], v[82:85]
	v_mfma_f32_16x16x32_f16 v[74:77], v[192:195], v[228:231], v[74:77]
	s_setprio 0
	s_barrier
	s_mov_b32 m0, s26
	s_mov_b32 s10, s50
	s_mov_b32 s11, s51
	ds_read_b128 v[196:199], v161 offset:16384
	ds_read_b128 v[204:207], v161 offset:18432
	ds_read_b128 v[208:211], v162 offset:16384
	ds_read_b128 v[212:215], v162 offset:18432
	ds_read_b128 v[216:219], v161 offset:20480
	ds_read_b128 v[220:223], v161 offset:22528
	ds_read_b128 v[224:227], v162 offset:20480
	ds_read_b128 v[228:231], v162 offset:22528
	buffer_load_dwordx4 v154, s[8:11], s62 offen lds
	s_mov_b32 m0, s27
	s_add_i32 s81, s62, 0x80000
	buffer_load_dwordx4 v156, s[8:11], s62 offen lds
	s_mov_b32 m0, s28
	s_nop 0
	buffer_load_dwordx4 v154, s[8:11], s81 offen lds
	s_mov_b32 m0, s29
	s_nop 0
	buffer_load_dwordx4 v156, s[8:11], s81 offen lds
	s_mov_b32 m0, s3
	s_nop 0
	buffer_load_dwordx4 v153, s[48:51], s78 offen lds
	s_mov_b32 m0, s30
	s_nop 0
	buffer_load_dwordx4 v155, s[48:51], s78 offen lds
	s_waitcnt vmcnt(8)
	s_waitcnt lgkmcnt(0)
	s_setprio 1
	s_waitcnt lgkmcnt(0)
	v_mfma_f32_16x16x32_f16 v[54:57], v[164:167], v[196:199], v[54:57]
	v_mfma_f32_16x16x32_f16 v[46:49], v[168:171], v[196:199], v[46:49]
	v_mfma_f32_16x16x32_f16 v[38:41], v[164:167], v[204:207], v[38:41]
	v_mfma_f32_16x16x32_f16 v[30:33], v[168:171], v[204:207], v[30:33]
	v_mfma_f32_16x16x32_f16 v[22:25], v[164:167], v[216:219], v[22:25]
	v_mfma_f32_16x16x32_f16 v[14:17], v[168:171], v[216:219], v[14:17]
	v_mfma_f32_16x16x32_f16 v[6:9], v[164:167], v[220:223], v[6:9]
	v_mfma_f32_16x16x32_f16 v[2:5], v[168:171], v[220:223], v[2:5]
	v_mfma_f32_16x16x32_f16 v[54:57], v[172:175], v[208:211], v[54:57]
	v_mfma_f32_16x16x32_f16 v[46:49], v[176:179], v[208:211], v[46:49]
	v_mfma_f32_16x16x32_f16 v[38:41], v[172:175], v[212:215], v[38:41]
	v_mfma_f32_16x16x32_f16 v[30:33], v[176:179], v[212:215], v[30:33]
	v_mfma_f32_16x16x32_f16 v[22:25], v[172:175], v[224:227], v[22:25]
	v_mfma_f32_16x16x32_f16 v[14:17], v[176:179], v[224:227], v[14:17]
	v_mfma_f32_16x16x32_f16 v[6:9], v[172:175], v[228:231], v[6:9]
	v_mfma_f32_16x16x32_f16 v[2:5], v[176:179], v[228:231], v[2:5]
	s_setprio 0
	s_setprio 1
	v_mfma_f32_16x16x32_f16 v[70:73], v[180:183], v[196:199], v[70:73]
	v_mfma_f32_16x16x32_f16 v[62:65], v[184:187], v[196:199], v[62:65]
	v_mfma_f32_16x16x32_f16 v[50:53], v[180:183], v[204:207], v[50:53]
	v_mfma_f32_16x16x32_f16 v[42:45], v[184:187], v[204:207], v[42:45]
	v_mfma_f32_16x16x32_f16 v[34:37], v[180:183], v[216:219], v[34:37]
	v_mfma_f32_16x16x32_f16 v[26:29], v[184:187], v[216:219], v[26:29]
	v_mfma_f32_16x16x32_f16 v[18:21], v[180:183], v[220:223], v[18:21]
	v_mfma_f32_16x16x32_f16 v[10:13], v[184:187], v[220:223], v[10:13]
	v_mfma_f32_16x16x32_f16 v[70:73], v[188:191], v[208:211], v[70:73]
	v_mfma_f32_16x16x32_f16 v[62:65], v[192:195], v[208:211], v[62:65]
	v_mfma_f32_16x16x32_f16 v[50:53], v[188:191], v[212:215], v[50:53]
	v_mfma_f32_16x16x32_f16 v[42:45], v[192:195], v[212:215], v[42:45]
	v_mfma_f32_16x16x32_f16 v[34:37], v[188:191], v[224:227], v[34:37]
	v_mfma_f32_16x16x32_f16 v[26:29], v[192:195], v[224:227], v[26:29]
	v_mfma_f32_16x16x32_f16 v[18:21], v[188:191], v[228:231], v[18:21]
	v_mfma_f32_16x16x32_f16 v[10:13], v[192:195], v[228:231], v[10:13]
	s_setprio 0
	s_barrier
	s_add_i32 s81, 0, 0x18000
	v_add_u32_e32 v0, s81, v157
	v_add_u32_e32 v147, s81, v158
	s_add_i32 s81, 0, 0x1c000
	ds_read_b128 v[164:167], v0
	ds_read_b128 v[168:171], v0 offset:2048
	ds_read_b128 v[172:175], v147
	ds_read_b128 v[176:179], v147 offset:2048
	v_add_u32_e32 v0, s81, v157
	v_add_u32_e32 v147, s81, v158
	ds_read_b128 v[180:183], v0
	ds_read_b128 v[184:187], v0 offset:2048
	ds_read_b128 v[188:191], v147
	ds_read_b128 v[192:195], v147 offset:2048
	s_add_i32 s78, s78, 0x80000
	s_mov_b32 m0, s31
	ds_read_b128 v[196:199], v161 offset:32768
	ds_read_b128 v[204:207], v161 offset:34816
	ds_read_b128 v[208:211], v162 offset:32768
	ds_read_b128 v[212:215], v162 offset:34816
	ds_read_b128 v[216:219], v161 offset:36864
	ds_read_b128 v[220:223], v161 offset:38912
	ds_read_b128 v[224:227], v162 offset:36864
	ds_read_b128 v[228:231], v162 offset:38912
	buffer_load_dwordx4 v153, s[48:51], s78 offen lds
	s_mov_b32 m0, s34
	s_nop 0
	buffer_load_dwordx4 v155, s[48:51], s78 offen lds
	s_waitcnt vmcnt(8)
	s_waitcnt lgkmcnt(0)
	s_setprio 1
	s_waitcnt lgkmcnt(0)
	v_mfma_f32_16x16x32_f16 v[118:121], v[164:167], v[196:199], v[118:121]
	v_mfma_f32_16x16x32_f16 v[110:113], v[168:171], v[196:199], v[110:113]
	v_mfma_f32_16x16x32_f16 v[102:105], v[164:167], v[204:207], v[102:105]
	v_mfma_f32_16x16x32_f16 v[94:97], v[168:171], v[204:207], v[94:97]
	v_mfma_f32_16x16x32_f16 v[86:89], v[164:167], v[216:219], v[86:89]
	v_mfma_f32_16x16x32_f16 v[78:81], v[168:171], v[216:219], v[78:81]
	v_mfma_f32_16x16x32_f16 v[66:69], v[164:167], v[220:223], v[66:69]
	v_mfma_f32_16x16x32_f16 v[58:61], v[168:171], v[220:223], v[58:61]
	v_mfma_f32_16x16x32_f16 v[118:121], v[172:175], v[208:211], v[118:121]
	v_mfma_f32_16x16x32_f16 v[110:113], v[176:179], v[208:211], v[110:113]
	v_mfma_f32_16x16x32_f16 v[102:105], v[172:175], v[212:215], v[102:105]
	v_mfma_f32_16x16x32_f16 v[94:97], v[176:179], v[212:215], v[94:97]
	v_mfma_f32_16x16x32_f16 v[86:89], v[172:175], v[224:227], v[86:89]
	v_mfma_f32_16x16x32_f16 v[78:81], v[176:179], v[224:227], v[78:81]
	v_mfma_f32_16x16x32_f16 v[66:69], v[172:175], v[228:231], v[66:69]
	v_mfma_f32_16x16x32_f16 v[58:61], v[176:179], v[228:231], v[58:61]
	s_setprio 0
	s_setprio 1
	v_mfma_f32_16x16x32_f16 v[126:129], v[180:183], v[196:199], v[126:129]
	v_mfma_f32_16x16x32_f16 v[122:125], v[184:187], v[196:199], v[122:125]
	v_mfma_f32_16x16x32_f16 v[114:117], v[180:183], v[204:207], v[114:117]
	v_mfma_f32_16x16x32_f16 v[106:109], v[184:187], v[204:207], v[106:109]
	v_mfma_f32_16x16x32_f16 v[98:101], v[180:183], v[216:219], v[98:101]
	v_mfma_f32_16x16x32_f16 v[90:93], v[184:187], v[216:219], v[90:93]
	v_mfma_f32_16x16x32_f16 v[82:85], v[180:183], v[220:223], v[82:85]
	v_mfma_f32_16x16x32_f16 v[74:77], v[184:187], v[220:223], v[74:77]
	v_mfma_f32_16x16x32_f16 v[126:129], v[188:191], v[208:211], v[126:129]
	v_mfma_f32_16x16x32_f16 v[122:125], v[192:195], v[208:211], v[122:125]
	v_mfma_f32_16x16x32_f16 v[114:117], v[188:191], v[212:215], v[114:117]
	v_mfma_f32_16x16x32_f16 v[106:109], v[192:195], v[212:215], v[106:109]
	v_mfma_f32_16x16x32_f16 v[98:101], v[188:191], v[224:227], v[98:101]
	v_mfma_f32_16x16x32_f16 v[90:93], v[192:195], v[224:227], v[90:93]
	v_mfma_f32_16x16x32_f16 v[82:85], v[188:191], v[228:231], v[82:85]
	v_mfma_f32_16x16x32_f16 v[74:77], v[192:195], v[228:231], v[74:77]
	s_setprio 0
	s_barrier
	s_mov_b32 m0, s35
	ds_read_b128 v[196:199], v161 offset:49152
	ds_read_b128 v[204:207], v161 offset:51200
	ds_read_b128 v[208:211], v162 offset:49152
	ds_read_b128 v[212:215], v162 offset:51200
	ds_read_b128 v[216:219], v161 offset:53248
	ds_read_b128 v[220:223], v161 offset:55296
	ds_read_b128 v[224:227], v162 offset:53248
	ds_read_b128 v[228:231], v162 offset:55296
	buffer_load_dwordx4 v154, s[8:11], s65 offen lds
	s_mov_b32 m0, s36
	s_add_i32 s62, s62, 0x80080
	buffer_load_dwordx4 v156, s[8:11], s65 offen lds
	s_mov_b32 m0, s39
	s_nop 0
	buffer_load_dwordx4 v154, s[8:11], s62 offen lds
	s_mov_b32 m0, s40
	s_nop 0
	buffer_load_dwordx4 v156, s[8:11], s62 offen lds
	s_mov_b32 m0, s37
	s_nop 0
	buffer_load_dwordx4 v153, s[48:51], s64 offen lds
	s_mov_b32 m0, s38
	s_nop 0
	buffer_load_dwordx4 v155, s[48:51], s64 offen lds
	s_waitcnt vmcnt(8)
	s_waitcnt lgkmcnt(0)
	s_setprio 1
	s_waitcnt lgkmcnt(0)
	v_mfma_f32_16x16x32_f16 v[54:57], v[164:167], v[196:199], v[54:57]
	v_mfma_f32_16x16x32_f16 v[46:49], v[168:171], v[196:199], v[46:49]
	v_mfma_f32_16x16x32_f16 v[38:41], v[164:167], v[204:207], v[38:41]
	v_mfma_f32_16x16x32_f16 v[30:33], v[168:171], v[204:207], v[30:33]
	v_mfma_f32_16x16x32_f16 v[22:25], v[164:167], v[216:219], v[22:25]
	v_mfma_f32_16x16x32_f16 v[14:17], v[168:171], v[216:219], v[14:17]
	v_mfma_f32_16x16x32_f16 v[6:9], v[164:167], v[220:223], v[6:9]
	v_mfma_f32_16x16x32_f16 v[2:5], v[168:171], v[220:223], v[2:5]
	v_mfma_f32_16x16x32_f16 v[54:57], v[172:175], v[208:211], v[54:57]
	v_mfma_f32_16x16x32_f16 v[46:49], v[176:179], v[208:211], v[46:49]
	v_mfma_f32_16x16x32_f16 v[38:41], v[172:175], v[212:215], v[38:41]
	v_mfma_f32_16x16x32_f16 v[30:33], v[176:179], v[212:215], v[30:33]
	v_mfma_f32_16x16x32_f16 v[22:25], v[172:175], v[224:227], v[22:25]
	v_mfma_f32_16x16x32_f16 v[14:17], v[176:179], v[224:227], v[14:17]
	v_mfma_f32_16x16x32_f16 v[6:9], v[172:175], v[228:231], v[6:9]
	v_mfma_f32_16x16x32_f16 v[2:5], v[176:179], v[228:231], v[2:5]
	s_setprio 0
	s_setprio 1
	v_mfma_f32_16x16x32_f16 v[70:73], v[180:183], v[196:199], v[70:73]
	v_mfma_f32_16x16x32_f16 v[62:65], v[184:187], v[196:199], v[62:65]
	v_mfma_f32_16x16x32_f16 v[50:53], v[180:183], v[204:207], v[50:53]
	v_mfma_f32_16x16x32_f16 v[42:45], v[184:187], v[204:207], v[42:45]
	v_mfma_f32_16x16x32_f16 v[34:37], v[180:183], v[216:219], v[34:37]
	v_mfma_f32_16x16x32_f16 v[26:29], v[184:187], v[216:219], v[26:29]
	v_mfma_f32_16x16x32_f16 v[18:21], v[180:183], v[220:223], v[18:21]
	v_mfma_f32_16x16x32_f16 v[10:13], v[184:187], v[220:223], v[10:13]
	v_mfma_f32_16x16x32_f16 v[70:73], v[188:191], v[208:211], v[70:73]
	v_mfma_f32_16x16x32_f16 v[62:65], v[192:195], v[208:211], v[62:65]
	v_mfma_f32_16x16x32_f16 v[50:53], v[188:191], v[212:215], v[50:53]
	v_mfma_f32_16x16x32_f16 v[42:45], v[192:195], v[212:215], v[42:45]
	v_mfma_f32_16x16x32_f16 v[34:37], v[188:191], v[224:227], v[34:37]
	v_mfma_f32_16x16x32_f16 v[26:29], v[192:195], v[224:227], v[26:29]
	v_mfma_f32_16x16x32_f16 v[18:21], v[188:191], v[228:231], v[18:21]
	v_mfma_f32_16x16x32_f16 v[10:13], v[192:195], v[228:231], v[10:13]
	s_setprio 0
	s_barrier
	s_branch .Lg1s_tail
.Lg1s_tbody:
	s_add_i32 s62, s58, 0xfff80080
	s_and_b64 s[10:11], s[10:11], exec
	s_cselect_b32 s78, s54, s62
	s_cselect_b32 s62, s55, s60
	s_add_i32 s10, 0, 0x10000
	v_add_u32_e32 v0, s10, v157
	v_add_u32_e32 v147, s10, v158
	s_add_i32 s10, 0, 0x14000
	ds_read_b128 v[164:167], v0
	ds_read_b128 v[168:171], v0 offset:2048
	ds_read_b128 v[172:175], v147
	ds_read_b128 v[176:179], v147 offset:2048
	v_add_u32_e32 v0, s10, v157
	v_add_u32_e32 v147, s10, v158
	ds_read_b128 v[180:183], v0
	ds_read_b128 v[184:187], v0 offset:2048
	ds_read_b128 v[188:191], v147
	ds_read_b128 v[192:195], v147 offset:2048
	s_or_b32 s64, s78, 0x80
	s_or_b32 s65, s62, 0x80
	s_mov_b32 m0, s41
	ds_read_b128 v[196:199], v161
	ds_read_b128 v[204:207], v161 offset:2048
	ds_read_b128 v[208:211], v162
	ds_read_b128 v[212:215], v162 offset:2048
	ds_read_b128 v[216:219], v161 offset:4096
	ds_read_b128 v[220:223], v161 offset:6144
	ds_read_b128 v[224:227], v162 offset:4096
	ds_read_b128 v[228:231], v162 offset:6144
	buffer_load_dwordx4 v153, s[48:51], s58 offen lds
	s_mov_b32 m0, s42
	s_nop 0
	buffer_load_dwordx4 v155, s[48:51], s58 offen lds
	s_waitcnt vmcnt(8)
	s_waitcnt lgkmcnt(0)
	s_barrier
	s_setprio 2
	s_waitcnt lgkmcnt(0)
	v_mfma_f32_16x16x32_f16 v[118:121], v[164:167], v[196:199], v[118:121]
	v_mfma_f32_16x16x32_f16 v[110:113], v[168:171], v[196:199], v[110:113]
	v_mfma_f32_16x16x32_f16 v[102:105], v[164:167], v[204:207], v[102:105]
	v_mfma_f32_16x16x32_f16 v[94:97], v[168:171], v[204:207], v[94:97]
	v_mfma_f32_16x16x32_f16 v[86:89], v[164:167], v[216:219], v[86:89]
	v_mfma_f32_16x16x32_f16 v[78:81], v[168:171], v[216:219], v[78:81]
	v_mfma_f32_16x16x32_f16 v[66:69], v[164:167], v[220:223], v[66:69]
	v_mfma_f32_16x16x32_f16 v[58:61], v[168:171], v[220:223], v[58:61]
	v_mfma_f32_16x16x32_f16 v[118:121], v[172:175], v[208:211], v[118:121]
	v_mfma_f32_16x16x32_f16 v[110:113], v[176:179], v[208:211], v[110:113]
	v_mfma_f32_16x16x32_f16 v[102:105], v[172:175], v[212:215], v[102:105]
	v_mfma_f32_16x16x32_f16 v[94:97], v[176:179], v[212:215], v[94:97]
	v_mfma_f32_16x16x32_f16 v[86:89], v[172:175], v[224:227], v[86:89]
	v_mfma_f32_16x16x32_f16 v[78:81], v[176:179], v[224:227], v[78:81]
	v_mfma_f32_16x16x32_f16 v[66:69], v[172:175], v[228:231], v[66:69]
	v_mfma_f32_16x16x32_f16 v[58:61], v[176:179], v[228:231], v[58:61]
	s_setprio 0
	s_setprio 2
	v_mfma_f32_16x16x32_f16 v[126:129], v[180:183], v[196:199], v[126:129]
	v_mfma_f32_16x16x32_f16 v[122:125], v[184:187], v[196:199], v[122:125]
	v_mfma_f32_16x16x32_f16 v[114:117], v[180:183], v[204:207], v[114:117]
	v_mfma_f32_16x16x32_f16 v[106:109], v[184:187], v[204:207], v[106:109]
	v_mfma_f32_16x16x32_f16 v[98:101], v[180:183], v[216:219], v[98:101]
	v_mfma_f32_16x16x32_f16 v[90:93], v[184:187], v[216:219], v[90:93]
	v_mfma_f32_16x16x32_f16 v[82:85], v[180:183], v[220:223], v[82:85]
	v_mfma_f32_16x16x32_f16 v[74:77], v[184:187], v[220:223], v[74:77]
	v_mfma_f32_16x16x32_f16 v[126:129], v[188:191], v[208:211], v[126:129]
	v_mfma_f32_16x16x32_f16 v[122:125], v[192:195], v[208:211], v[122:125]
	v_mfma_f32_16x16x32_f16 v[114:117], v[188:191], v[212:215], v[114:117]
	v_mfma_f32_16x16x32_f16 v[106:109], v[192:195], v[212:215], v[106:109]
	v_mfma_f32_16x16x32_f16 v[98:101], v[188:191], v[224:227], v[98:101]
	v_mfma_f32_16x16x32_f16 v[90:93], v[192:195], v[224:227], v[90:93]
	v_mfma_f32_16x16x32_f16 v[82:85], v[188:191], v[228:231], v[82:85]
	v_mfma_f32_16x16x32_f16 v[74:77], v[192:195], v[228:231], v[74:77]
	s_setprio 0
	s_mov_b32 m0, s26
	s_mov_b32 s10, s50
	s_mov_b32 s11, s51
	ds_read_b128 v[196:199], v161 offset:16384
	ds_read_b128 v[204:207], v161 offset:18432
	ds_read_b128 v[208:211], v162 offset:16384
	ds_read_b128 v[212:215], v162 offset:18432
	ds_read_b128 v[216:219], v161 offset:20480
	ds_read_b128 v[220:223], v161 offset:22528
	ds_read_b128 v[224:227], v162 offset:20480
	ds_read_b128 v[228:231], v162 offset:22528
	buffer_load_dwordx4 v154, s[8:11], s62 offen lds
	s_mov_b32 m0, s27
	s_add_i32 s81, s62, 0x80000
	buffer_load_dwordx4 v156, s[8:11], s62 offen lds
	s_mov_b32 m0, s28
	s_nop 0
	buffer_load_dwordx4 v154, s[8:11], s81 offen lds
	s_mov_b32 m0, s29
	s_nop 0
	buffer_load_dwordx4 v156, s[8:11], s81 offen lds
	s_mov_b32 m0, s3
	s_nop 0
	buffer_load_dwordx4 v153, s[48:51], s78 offen lds
	s_mov_b32 m0, s30
	s_nop 0
	buffer_load_dwordx4 v155, s[48:51], s78 offen lds
	s_waitcnt vmcnt(8)
	s_waitcnt lgkmcnt(0)
	s_barrier
	s_setprio 2
	s_waitcnt lgkmcnt(0)
	v_mfma_f32_16x16x32_f16 v[54:57], v[164:167], v[196:199], v[54:57]
	v_mfma_f32_16x16x32_f16 v[46:49], v[168:171], v[196:199], v[46:49]
	v_mfma_f32_16x16x32_f16 v[38:41], v[164:167], v[204:207], v[38:41]
	v_mfma_f32_16x16x32_f16 v[30:33], v[168:171], v[204:207], v[30:33]
	v_mfma_f32_16x16x32_f16 v[22:25], v[164:167], v[216:219], v[22:25]
	v_mfma_f32_16x16x32_f16 v[14:17], v[168:171], v[216:219], v[14:17]
	v_mfma_f32_16x16x32_f16 v[6:9], v[164:167], v[220:223], v[6:9]
	v_mfma_f32_16x16x32_f16 v[2:5], v[168:171], v[220:223], v[2:5]
	v_mfma_f32_16x16x32_f16 v[54:57], v[172:175], v[208:211], v[54:57]
	v_mfma_f32_16x16x32_f16 v[46:49], v[176:179], v[208:211], v[46:49]
	v_mfma_f32_16x16x32_f16 v[38:41], v[172:175], v[212:215], v[38:41]
	v_mfma_f32_16x16x32_f16 v[30:33], v[176:179], v[212:215], v[30:33]
	v_mfma_f32_16x16x32_f16 v[22:25], v[172:175], v[224:227], v[22:25]
	v_mfma_f32_16x16x32_f16 v[14:17], v[176:179], v[224:227], v[14:17]
	v_mfma_f32_16x16x32_f16 v[6:9], v[172:175], v[228:231], v[6:9]
	v_mfma_f32_16x16x32_f16 v[2:5], v[176:179], v[228:231], v[2:5]
	s_setprio 0
	s_setprio 2
	v_mfma_f32_16x16x32_f16 v[70:73], v[180:183], v[196:199], v[70:73]
	v_mfma_f32_16x16x32_f16 v[62:65], v[184:187], v[196:199], v[62:65]
	v_mfma_f32_16x16x32_f16 v[50:53], v[180:183], v[204:207], v[50:53]
	v_mfma_f32_16x16x32_f16 v[42:45], v[184:187], v[204:207], v[42:45]
	v_mfma_f32_16x16x32_f16 v[34:37], v[180:183], v[216:219], v[34:37]
	v_mfma_f32_16x16x32_f16 v[26:29], v[184:187], v[216:219], v[26:29]
	v_mfma_f32_16x16x32_f16 v[18:21], v[180:183], v[220:223], v[18:21]
	v_mfma_f32_16x16x32_f16 v[10:13], v[184:187], v[220:223], v[10:13]
	v_mfma_f32_16x16x32_f16 v[70:73], v[188:191], v[208:211], v[70:73]
	v_mfma_f32_16x16x32_f16 v[62:65], v[192:195], v[208:211], v[62:65]
	v_mfma_f32_16x16x32_f16 v[50:53], v[188:191], v[212:215], v[50:53]
	v_mfma_f32_16x16x32_f16 v[42:45], v[192:195], v[212:215], v[42:45]
	v_mfma_f32_16x16x32_f16 v[34:37], v[188:191], v[224:227], v[34:37]
	v_mfma_f32_16x16x32_f16 v[26:29], v[192:195], v[224:227], v[26:29]
	v_mfma_f32_16x16x32_f16 v[18:21], v[188:191], v[228:231], v[18:21]
	v_mfma_f32_16x16x32_f16 v[10:13], v[192:195], v[228:231], v[10:13]
	s_setprio 0
	s_add_i32 s81, 0, 0x18000
	v_add_u32_e32 v0, s81, v157
	v_add_u32_e32 v147, s81, v158
	s_add_i32 s81, 0, 0x1c000
	ds_read_b128 v[164:167], v0
	ds_read_b128 v[168:171], v0 offset:2048
	ds_read_b128 v[172:175], v147
	ds_read_b128 v[176:179], v147 offset:2048
	v_add_u32_e32 v0, s81, v157
	v_add_u32_e32 v147, s81, v158
	ds_read_b128 v[180:183], v0
	ds_read_b128 v[184:187], v0 offset:2048
	ds_read_b128 v[188:191], v147
	ds_read_b128 v[192:195], v147 offset:2048
	s_add_i32 s78, s78, 0x80000
	s_mov_b32 m0, s31
	ds_read_b128 v[196:199], v161 offset:32768
	ds_read_b128 v[204:207], v161 offset:34816
	ds_read_b128 v[208:211], v162 offset:32768
	ds_read_b128 v[212:215], v162 offset:34816
	ds_read_b128 v[216:219], v161 offset:36864
	ds_read_b128 v[220:223], v161 offset:38912
	ds_read_b128 v[224:227], v162 offset:36864
	ds_read_b128 v[228:231], v162 offset:38912
	buffer_load_dwordx4 v153, s[48:51], s78 offen lds
	s_mov_b32 m0, s34
	s_nop 0
	buffer_load_dwordx4 v155, s[48:51], s78 offen lds
	s_waitcnt vmcnt(8)
	s_waitcnt lgkmcnt(0)
	s_barrier
	s_setprio 2
	s_waitcnt lgkmcnt(0)
	v_mfma_f32_16x16x32_f16 v[118:121], v[164:167], v[196:199], v[118:121]
	v_mfma_f32_16x16x32_f16 v[110:113], v[168:171], v[196:199], v[110:113]
	v_mfma_f32_16x16x32_f16 v[102:105], v[164:167], v[204:207], v[102:105]
	v_mfma_f32_16x16x32_f16 v[94:97], v[168:171], v[204:207], v[94:97]
	v_mfma_f32_16x16x32_f16 v[86:89], v[164:167], v[216:219], v[86:89]
	v_mfma_f32_16x16x32_f16 v[78:81], v[168:171], v[216:219], v[78:81]
	v_mfma_f32_16x16x32_f16 v[66:69], v[164:167], v[220:223], v[66:69]
	v_mfma_f32_16x16x32_f16 v[58:61], v[168:171], v[220:223], v[58:61]
	v_mfma_f32_16x16x32_f16 v[118:121], v[172:175], v[208:211], v[118:121]
	v_mfma_f32_16x16x32_f16 v[110:113], v[176:179], v[208:211], v[110:113]
	v_mfma_f32_16x16x32_f16 v[102:105], v[172:175], v[212:215], v[102:105]
	v_mfma_f32_16x16x32_f16 v[94:97], v[176:179], v[212:215], v[94:97]
	v_mfma_f32_16x16x32_f16 v[86:89], v[172:175], v[224:227], v[86:89]
	v_mfma_f32_16x16x32_f16 v[78:81], v[176:179], v[224:227], v[78:81]
	v_mfma_f32_16x16x32_f16 v[66:69], v[172:175], v[228:231], v[66:69]
	v_mfma_f32_16x16x32_f16 v[58:61], v[176:179], v[228:231], v[58:61]
	s_setprio 0
	s_setprio 2
	v_mfma_f32_16x16x32_f16 v[126:129], v[180:183], v[196:199], v[126:129]
	v_mfma_f32_16x16x32_f16 v[122:125], v[184:187], v[196:199], v[122:125]
	v_mfma_f32_16x16x32_f16 v[114:117], v[180:183], v[204:207], v[114:117]
	v_mfma_f32_16x16x32_f16 v[106:109], v[184:187], v[204:207], v[106:109]
	v_mfma_f32_16x16x32_f16 v[98:101], v[180:183], v[216:219], v[98:101]
	v_mfma_f32_16x16x32_f16 v[90:93], v[184:187], v[216:219], v[90:93]
	v_mfma_f32_16x16x32_f16 v[82:85], v[180:183], v[220:223], v[82:85]
	v_mfma_f32_16x16x32_f16 v[74:77], v[184:187], v[220:223], v[74:77]
	v_mfma_f32_16x16x32_f16 v[126:129], v[188:191], v[208:211], v[126:129]
	v_mfma_f32_16x16x32_f16 v[122:125], v[192:195], v[208:211], v[122:125]
	v_mfma_f32_16x16x32_f16 v[114:117], v[188:191], v[212:215], v[114:117]
	v_mfma_f32_16x16x32_f16 v[106:109], v[192:195], v[212:215], v[106:109]
	v_mfma_f32_16x16x32_f16 v[98:101], v[188:191], v[224:227], v[98:101]
	v_mfma_f32_16x16x32_f16 v[90:93], v[192:195], v[224:227], v[90:93]
	v_mfma_f32_16x16x32_f16 v[82:85], v[188:191], v[228:231], v[82:85]
	v_mfma_f32_16x16x32_f16 v[74:77], v[192:195], v[228:231], v[74:77]
	s_setprio 0
	s_mov_b32 m0, s35
	ds_read_b128 v[196:199], v161 offset:49152
	ds_read_b128 v[204:207], v161 offset:51200
	ds_read_b128 v[208:211], v162 offset:49152
	ds_read_b128 v[212:215], v162 offset:51200
	ds_read_b128 v[216:219], v161 offset:53248
	ds_read_b128 v[220:223], v161 offset:55296
	ds_read_b128 v[224:227], v162 offset:53248
	ds_read_b128 v[228:231], v162 offset:55296
	buffer_load_dwordx4 v154, s[8:11], s65 offen lds
	s_mov_b32 m0, s36
	s_add_i32 s62, s62, 0x80080
	buffer_load_dwordx4 v156, s[8:11], s65 offen lds
	s_mov_b32 m0, s39
	s_nop 0
	buffer_load_dwordx4 v154, s[8:11], s62 offen lds
	s_mov_b32 m0, s40
	s_nop 0
	buffer_load_dwordx4 v156, s[8:11], s62 offen lds
	s_mov_b32 m0, s37
	s_nop 0
	buffer_load_dwordx4 v153, s[48:51], s64 offen lds
	s_mov_b32 m0, s38
	s_nop 0
	buffer_load_dwordx4 v155, s[48:51], s64 offen lds
	s_waitcnt vmcnt(8)
	s_waitcnt lgkmcnt(0)
	s_barrier
	s_setprio 2
	s_waitcnt lgkmcnt(0)
	v_mfma_f32_16x16x32_f16 v[54:57], v[164:167], v[196:199], v[54:57]
	v_mfma_f32_16x16x32_f16 v[46:49], v[168:171], v[196:199], v[46:49]
	v_mfma_f32_16x16x32_f16 v[38:41], v[164:167], v[204:207], v[38:41]
	v_mfma_f32_16x16x32_f16 v[30:33], v[168:171], v[204:207], v[30:33]
	v_mfma_f32_16x16x32_f16 v[22:25], v[164:167], v[216:219], v[22:25]
	v_mfma_f32_16x16x32_f16 v[14:17], v[168:171], v[216:219], v[14:17]
	v_mfma_f32_16x16x32_f16 v[6:9], v[164:167], v[220:223], v[6:9]
	v_mfma_f32_16x16x32_f16 v[2:5], v[168:171], v[220:223], v[2:5]
	v_mfma_f32_16x16x32_f16 v[54:57], v[172:175], v[208:211], v[54:57]
	v_mfma_f32_16x16x32_f16 v[46:49], v[176:179], v[208:211], v[46:49]
	v_mfma_f32_16x16x32_f16 v[38:41], v[172:175], v[212:215], v[38:41]
	v_mfma_f32_16x16x32_f16 v[30:33], v[176:179], v[212:215], v[30:33]
	v_mfma_f32_16x16x32_f16 v[22:25], v[172:175], v[224:227], v[22:25]
	v_mfma_f32_16x16x32_f16 v[14:17], v[176:179], v[224:227], v[14:17]
	v_mfma_f32_16x16x32_f16 v[6:9], v[172:175], v[228:231], v[6:9]
	v_mfma_f32_16x16x32_f16 v[2:5], v[176:179], v[228:231], v[2:5]
	s_setprio 0
	s_setprio 2
	v_mfma_f32_16x16x32_f16 v[70:73], v[180:183], v[196:199], v[70:73]
	v_mfma_f32_16x16x32_f16 v[62:65], v[184:187], v[196:199], v[62:65]
	v_mfma_f32_16x16x32_f16 v[50:53], v[180:183], v[204:207], v[50:53]
	v_mfma_f32_16x16x32_f16 v[42:45], v[184:187], v[204:207], v[42:45]
	v_mfma_f32_16x16x32_f16 v[34:37], v[180:183], v[216:219], v[34:37]
	v_mfma_f32_16x16x32_f16 v[26:29], v[184:187], v[216:219], v[26:29]
	v_mfma_f32_16x16x32_f16 v[18:21], v[180:183], v[220:223], v[18:21]
	v_mfma_f32_16x16x32_f16 v[10:13], v[184:187], v[220:223], v[10:13]
	v_mfma_f32_16x16x32_f16 v[70:73], v[188:191], v[208:211], v[70:73]
	v_mfma_f32_16x16x32_f16 v[62:65], v[192:195], v[208:211], v[62:65]
	v_mfma_f32_16x16x32_f16 v[50:53], v[188:191], v[212:215], v[50:53]
	v_mfma_f32_16x16x32_f16 v[42:45], v[192:195], v[212:215], v[42:45]
	v_mfma_f32_16x16x32_f16 v[34:37], v[188:191], v[224:227], v[34:37]
	v_mfma_f32_16x16x32_f16 v[26:29], v[192:195], v[224:227], v[26:29]
	v_mfma_f32_16x16x32_f16 v[18:21], v[188:191], v[228:231], v[18:21]
	v_mfma_f32_16x16x32_f16 v[10:13], v[192:195], v[228:231], v[10:13]
	s_setprio 0
.Lg1s_tail:
	s_add_i32 s61, s61, 2
	s_addk_i32 s58, 0x100
	s_addk_i32 s60, 0x100
	s_cmp_gt_u32 s61, 29
	s_cbranch_scc1 .LBB0_145

.LBB0_147:
	s_waitcnt vmcnt(16)
	v_pk_mul_f32 v[128:129], v[120:121], v[128:129]
	v_alignbit_b32 v0, v131, v130, 24
	v_and_b32_e32 v147, 0xffffff, v130
	v_cvt_f32_u32_e32 v0, v0
	v_cvt_f32_u32_e32 v147, v147
	v_and_b32_e32 v148, 0xffffff, v144
	v_cvt_f32_u32_e32 v148, v148
	v_lshl_or_b32 v150, s53, 7, v160
	v_fmac_f32_e32 v0, 0x33800000, v147
	v_fmamk_f32 v0, v0, 0x3a000000, v200
	v_rsq_f32_e32 v167, v0
	v_alignbit_b32 v0, v133, v132, 24
	v_and_b32_e32 v147, 0xffffff, v132
	v_cvt_f32_u32_e32 v0, v0
	v_cvt_f32_u32_e32 v147, v147
	v_mul_f32_e32 v172, 0xbfb8aa3b, v167
	v_pk_mul_f32 v[174:175], v[118:119], v[172:173] op_sel_hi:[1,0]
	v_mul_f32_e32 v170, v167, v167
	v_fmac_f32_e32 v0, 0x33800000, v147
	v_fmamk_f32 v0, v0, 0x3a000000, v200
	v_rsq_f32_e32 v171, v0
	v_alignbit_b32 v0, v135, v134, 24
	v_and_b32_e32 v147, 0xffffff, v134
	v_cvt_f32_u32_e32 v0, v0
	v_cvt_f32_u32_e32 v147, v147
	v_exp_f32_e32 v174, v174
	v_exp_f32_e32 v175, v175
	v_pk_mul_f32 v[118:119], v[118:119], v[126:127]
	v_fmac_f32_e32 v0, 0x33800000, v147
	v_fmamk_f32 v0, v0, 0x3a000000, v200
	v_rsq_f32_e32 v166, v0
	v_alignbit_b32 v0, v137, v136, 24
	v_and_b32_e32 v147, 0xffffff, v136
	v_cvt_f32_u32_e32 v0, v0
	v_cvt_f32_u32_e32 v147, v147
	v_pk_add_f32 v[174:175], v[174:175], 1.0 op_sel_hi:[1,0]
	v_pk_mul_f32 v[120:121], v[120:121], v[172:173] op_sel_hi:[1,0]
	v_rcp_f32_e32 v174, v174
	v_fmac_f32_e32 v0, 0x33800000, v147
	v_fmamk_f32 v0, v0, 0x3a000000, v200
	v_rsq_f32_e32 v165, v0
	v_alignbit_b32 v0, v139, v138, 24
	v_and_b32_e32 v147, 0xffffff, v138
	v_rcp_f32_e32 v175, v175
	v_cvt_f32_u32_e32 v0, v0
	v_cvt_f32_u32_e32 v147, v147
	v_exp_f32_e32 v120, v120
	v_pk_mul_f32 v[126:127], v[170:171], v[174:175] op_sel_hi:[0,1]
	v_pk_mul_f32 v[118:119], v[118:119], v[126:127]
	v_fmac_f32_e32 v0, 0x33800000, v147
	v_pk_mul_f32 v[126:127], v[110:111], v[172:173] op_sel_hi:[1,0]
	v_fmamk_f32 v0, v0, 0x3a000000, v200
	v_exp_f32_e32 v126, v126
	v_exp_f32_e32 v127, v127
	v_rsq_f32_e32 v164, v0
	v_alignbit_b32 v0, v141, v140, 24
	v_and_b32_e32 v147, 0xffffff, v140
	v_cvt_f32_u32_e32 v0, v0
	v_cvt_f32_u32_e32 v147, v147
	v_pk_add_f32 v[126:127], v[126:127], 1.0 op_sel_hi:[1,0]
	v_pk_mul_f32 v[110:111], v[110:111], v[122:123]
	v_rcp_f32_e32 v126, v126
	v_rcp_f32_e32 v127, v127
	v_fmac_f32_e32 v0, 0x33800000, v147
	v_fmamk_f32 v0, v0, 0x3a000000, v200
	v_rsq_f32_e32 v163, v0
	v_alignbit_b32 v0, v143, v142, 24
	v_and_b32_e32 v147, 0xffffff, v142
	v_cvt_f32_u32_e32 v0, v0
	v_cvt_f32_u32_e32 v147, v147
	v_pk_mul_f32 v[122:123], v[170:171], v[126:127] op_sel_hi:[0,1]
	v_pk_mul_f32 v[122:123], v[110:111], v[122:123]
	v_pk_mul_f32 v[110:111], v[112:113], v[172:173] op_sel_hi:[1,0]
	v_exp_f32_e32 v121, v121
	v_exp_f32_e32 v110, v110
	v_exp_f32_e32 v111, v111
	v_fmac_f32_e32 v0, 0x33800000, v147
	v_fmamk_f32 v0, v0, 0x3a000000, v200
	v_rsq_f32_e32 v147, v0
	v_alignbit_b32 v0, v145, v144, 24
	v_pk_add_f32 v[120:121], v[120:121], 1.0 op_sel_hi:[1,0]
	v_pk_add_f32 v[110:111], v[110:111], 1.0 op_sel_hi:[1,0]
	v_cvt_f32_u32_e32 v0, v0
	v_rcp_f32_e32 v120, v120
	v_rcp_f32_e32 v121, v121
	v_rcp_f32_e32 v110, v110
	v_rcp_f32_e32 v111, v111
	v_fmac_f32_e32 v0, 0x33800000, v148
	v_ashrrev_i32_e32 v151, 31, v150
	v_mov_b64_e32 v[148:149], s[16:17]
	v_pk_mul_f32 v[120:121], v[170:171], v[120:121] op_sel_hi:[0,1]
	v_pk_mul_f32 v[124:125], v[112:113], v[124:125]
	v_pk_mul_f32 v[110:111], v[170:171], v[110:111] op_sel_hi:[0,1]
	v_mad_i64_i32 v[168:169], s[10:11], v146, s99, v[148:149]
	v_pk_mul_f32 v[120:121], v[128:129], v[120:121]
	v_pk_mul_f32 v[112:113], v[124:125], v[110:111]
	v_lshlrev_b64 v[110:111], 1, v[150:151]
	v_lshl_add_u64 v[124:125], v[168:169], 0, v[110:111]
	v_cvt_pk_bf16_f32 v118, v118, v119
	v_cvt_pk_bf16_f32 v119, v120, v121
	v_cvt_pk_bf16_f32 v120, v122, v123
	v_cvt_pk_bf16_f32 v121, v112, v113
	global_store_dwordx4 v[124:125], v[118:121], off
	v_pk_mul_f32 v[116:117], v[104:105], v[116:117]
	v_pk_mul_f32 v[108:109], v[96:97], v[108:109]
	v_mul_f32_e32 v120, 0xbfb8aa3b, v171
	v_pk_mul_f32 v[122:123], v[102:103], v[120:121] op_sel_hi:[1,0]
	v_mul_f32_e32 v118, v171, v171
	v_exp_f32_e32 v122, v122
	v_exp_f32_e32 v123, v123
	v_pk_mul_f32 v[102:103], v[102:103], v[114:115]
	v_pk_mul_f32 v[104:105], v[104:105], v[120:121] op_sel_hi:[1,0]
	v_or_b32_e32 v112, 16, v146
	v_pk_add_f32 v[122:123], v[122:123], 1.0 op_sel_hi:[1,0]
	v_exp_f32_e32 v104, v104
	v_rcp_f32_e32 v122, v122
	v_rcp_f32_e32 v123, v123
	v_exp_f32_e32 v105, v105
	v_mad_i64_i32 v[112:113], s[10:11], v112, s99, v[148:149]
	v_pk_mul_f32 v[114:115], v[118:119], v[122:123] op_sel_hi:[0,1]
	v_pk_mul_f32 v[102:103], v[102:103], v[114:115]
	v_pk_mul_f32 v[114:115], v[94:95], v[120:121] op_sel_hi:[1,0]
	v_pk_mul_f32 v[94:95], v[94:95], v[106:107]
	v_exp_f32_e32 v114, v114
	v_exp_f32_e32 v115, v115
	v_pk_add_f32 v[104:105], v[104:105], 1.0 op_sel_hi:[1,0]
	v_lshl_add_u64 v[112:113], v[112:113], 0, v[110:111]
	v_rcp_f32_e32 v104, v104
	v_pk_add_f32 v[114:115], v[114:115], 1.0 op_sel_hi:[1,0]
	v_rcp_f32_e32 v105, v105
	v_rcp_f32_e32 v114, v114
	v_rcp_f32_e32 v115, v115
	v_pk_mul_f32 v[100:101], v[88:89], v[100:101]
	v_pk_mul_f32 v[104:105], v[118:119], v[104:105] op_sel_hi:[0,1]
	v_pk_mul_f32 v[104:105], v[116:117], v[104:105]
	v_pk_mul_f32 v[106:107], v[118:119], v[114:115] op_sel_hi:[0,1]
	v_pk_mul_f32 v[106:107], v[94:95], v[106:107]
	v_pk_mul_f32 v[94:95], v[96:97], v[120:121] op_sel_hi:[1,0]
	v_pk_mul_f32 v[92:93], v[80:81], v[92:93]
	v_exp_f32_e32 v94, v94
	v_exp_f32_e32 v95, v95
	v_pk_mul_f32 v[84:85], v[68:69], v[84:85]
	v_pk_mul_f32 v[76:77], v[60:61], v[76:77]
	v_pk_mul_f32 v[72:73], v[56:57], v[72:73]
	v_pk_add_f32 v[94:95], v[94:95], 1.0 op_sel_hi:[1,0]
	v_pk_mul_f32 v[64:65], v[48:49], v[64:65]
	v_rcp_f32_e32 v94, v94
	v_rcp_f32_e32 v95, v95
	v_pk_mul_f32 v[52:53], v[40:41], v[52:53]
	v_pk_mul_f32 v[44:45], v[32:33], v[44:45]
	v_pk_mul_f32 v[36:37], v[24:25], v[36:37]
	v_pk_mul_f32 v[94:95], v[118:119], v[94:95] op_sel_hi:[0,1]
	v_pk_mul_f32 v[108:109], v[108:109], v[94:95]
	v_cvt_pk_bf16_f32 v94, v102, v103
	v_mul_f32_e32 v102, 0xbfb8aa3b, v166
	v_cvt_pk_bf16_f32 v95, v104, v105
	v_pk_mul_f32 v[104:105], v[86:87], v[102:103] op_sel_hi:[1,0]
	v_cvt_pk_bf16_f32 v96, v106, v107
	v_cvt_pk_bf16_f32 v97, v108, v109
	global_store_dwordx4 v[112:113], v[94:97], off
	v_exp_f32_e32 v104, v104
	v_exp_f32_e32 v105, v105
	v_mul_f32_e32 v96, v166, v166
	v_pk_mul_f32 v[86:87], v[86:87], v[98:99]
	v_pk_mul_f32 v[88:89], v[88:89], v[102:103] op_sel_hi:[1,0]
	v_pk_add_f32 v[104:105], v[104:105], 1.0 op_sel_hi:[1,0]
	v_exp_f32_e32 v88, v88
	v_rcp_f32_e32 v104, v104
	v_rcp_f32_e32 v105, v105
	v_exp_f32_e32 v89, v89
	v_or_b32_e32 v94, 32, v146
	v_mad_i64_i32 v[94:95], s[10:11], v94, s99, v[148:149]
	v_pk_mul_f32 v[98:99], v[96:97], v[104:105] op_sel_hi:[0,1]
	v_pk_mul_f32 v[86:87], v[86:87], v[98:99]
	v_pk_mul_f32 v[98:99], v[78:79], v[102:103] op_sel_hi:[1,0]
	v_pk_mul_f32 v[78:79], v[78:79], v[90:91]
	v_exp_f32_e32 v98, v98
	v_exp_f32_e32 v99, v99
	v_pk_add_f32 v[88:89], v[88:89], 1.0 op_sel_hi:[1,0]
	v_lshl_add_u64 v[94:95], v[94:95], 0, v[110:111]
	v_rcp_f32_e32 v88, v88
	v_pk_add_f32 v[98:99], v[98:99], 1.0 op_sel_hi:[1,0]
	v_rcp_f32_e32 v89, v89
	v_rcp_f32_e32 v98, v98
	v_rcp_f32_e32 v99, v99
	v_fmamk_f32 v0, v0, 0x3a000000, v200
	v_pk_mul_f32 v[88:89], v[96:97], v[88:89] op_sel_hi:[0,1]
	v_pk_mul_f32 v[88:89], v[100:101], v[88:89]
	v_pk_mul_f32 v[90:91], v[96:97], v[98:99] op_sel_hi:[0,1]
	v_pk_mul_f32 v[90:91], v[78:79], v[90:91]
	v_pk_mul_f32 v[78:79], v[80:81], v[102:103] op_sel_hi:[1,0]
	v_rsq_f32_e32 v0, v0
	v_exp_f32_e32 v78, v78
	v_exp_f32_e32 v79, v79
	v_pk_mul_f32 v[28:29], v[16:17], v[28:29]
	v_pk_mul_f32 v[20:21], v[8:9], v[20:21]
	v_pk_mul_f32 v[12:13], v[4:5], v[12:13]
	v_pk_add_f32 v[78:79], v[78:79], 1.0 op_sel_hi:[1,0]
	s_andn2_b64 vcc, exec, s[4:5]
	v_rcp_f32_e32 v78, v78
	v_rcp_f32_e32 v79, v79
	s_nop 0
	v_pk_mul_f32 v[78:79], v[96:97], v[78:79] op_sel_hi:[0,1]
	v_pk_mul_f32 v[92:93], v[92:93], v[78:79]
	v_cvt_pk_bf16_f32 v78, v86, v87
	v_mul_f32_e32 v86, 0xbfb8aa3b, v165
	v_cvt_pk_bf16_f32 v79, v88, v89
	v_pk_mul_f32 v[88:89], v[66:67], v[86:87] op_sel_hi:[1,0]
	v_cvt_pk_bf16_f32 v80, v90, v91
	v_cvt_pk_bf16_f32 v81, v92, v93
	global_store_dwordx4 v[94:95], v[78:81], off
	v_exp_f32_e32 v88, v88
	v_exp_f32_e32 v89, v89
	v_mul_f32_e32 v80, v165, v165
	v_pk_mul_f32 v[66:67], v[66:67], v[82:83]
	v_pk_mul_f32 v[68:69], v[68:69], v[86:87] op_sel_hi:[1,0]
	v_pk_add_f32 v[88:89], v[88:89], 1.0 op_sel_hi:[1,0]
	v_exp_f32_e32 v68, v68
	v_rcp_f32_e32 v88, v88
	v_rcp_f32_e32 v89, v89
	v_exp_f32_e32 v69, v69
	v_or_b32_e32 v78, 48, v146
	v_mad_i64_i32 v[78:79], s[10:11], v78, s99, v[148:149]
	v_pk_mul_f32 v[82:83], v[80:81], v[88:89] op_sel_hi:[0,1]
	v_pk_mul_f32 v[66:67], v[66:67], v[82:83]
	v_pk_mul_f32 v[82:83], v[58:59], v[86:87] op_sel_hi:[1,0]
	v_pk_mul_f32 v[58:59], v[58:59], v[74:75]
	v_exp_f32_e32 v82, v82
	v_exp_f32_e32 v83, v83
	v_pk_add_f32 v[68:69], v[68:69], 1.0 op_sel_hi:[1,0]
	v_lshl_add_u64 v[78:79], v[78:79], 0, v[110:111]
	v_rcp_f32_e32 v68, v68
	v_pk_add_f32 v[82:83], v[82:83], 1.0 op_sel_hi:[1,0]
	v_rcp_f32_e32 v69, v69
	v_rcp_f32_e32 v82, v82
	v_rcp_f32_e32 v83, v83
	v_pk_mul_f32 v[68:69], v[80:81], v[68:69] op_sel_hi:[0,1]
	v_pk_mul_f32 v[68:69], v[84:85], v[68:69]
	v_pk_mul_f32 v[74:75], v[80:81], v[82:83] op_sel_hi:[0,1]
	v_pk_mul_f32 v[74:75], v[58:59], v[74:75]
	v_pk_mul_f32 v[58:59], v[60:61], v[86:87] op_sel_hi:[1,0]
	s_nop 0
	v_exp_f32_e32 v58, v58
	v_exp_f32_e32 v59, v59
	s_nop 0
	v_pk_add_f32 v[58:59], v[58:59], 1.0 op_sel_hi:[1,0]
	s_nop 0
	v_rcp_f32_e32 v58, v58
	v_rcp_f32_e32 v59, v59
	s_nop 0
	v_pk_mul_f32 v[58:59], v[80:81], v[58:59] op_sel_hi:[0,1]
	v_pk_mul_f32 v[76:77], v[76:77], v[58:59]
	v_cvt_pk_bf16_f32 v58, v66, v67
	v_mul_f32_e32 v66, 0xbfb8aa3b, v164
	v_cvt_pk_bf16_f32 v59, v68, v69
	v_pk_mul_f32 v[68:69], v[54:55], v[66:67] op_sel_hi:[1,0]
	v_cvt_pk_bf16_f32 v60, v74, v75
	v_cvt_pk_bf16_f32 v61, v76, v77
	global_store_dwordx4 v[78:79], v[58:61], off
	v_exp_f32_e32 v68, v68
	v_exp_f32_e32 v69, v69
	v_mul_f32_e32 v60, v164, v164
	v_pk_mul_f32 v[54:55], v[54:55], v[70:71]
	v_pk_mul_f32 v[56:57], v[56:57], v[66:67] op_sel_hi:[1,0]
	v_pk_add_f32 v[68:69], v[68:69], 1.0 op_sel_hi:[1,0]
	v_exp_f32_e32 v56, v56
	v_rcp_f32_e32 v68, v68
	v_rcp_f32_e32 v69, v69
	v_exp_f32_e32 v57, v57
	v_add_u32_e32 v58, 0x80, v146
	v_mad_i64_i32 v[58:59], s[10:11], v58, s99, v[148:149]
	v_pk_mul_f32 v[68:69], v[60:61], v[68:69] op_sel_hi:[0,1]
	v_pk_mul_f32 v[54:55], v[54:55], v[68:69]
	v_pk_mul_f32 v[68:69], v[46:47], v[66:67] op_sel_hi:[1,0]
	v_pk_mul_f32 v[46:47], v[46:47], v[62:63]
	v_exp_f32_e32 v68, v68
	v_exp_f32_e32 v69, v69
	v_pk_add_f32 v[56:57], v[56:57], 1.0 op_sel_hi:[1,0]
	v_lshl_add_u64 v[58:59], v[58:59], 0, v[110:111]
	v_rcp_f32_e32 v56, v56
	v_pk_add_f32 v[68:69], v[68:69], 1.0 op_sel_hi:[1,0]
	v_rcp_f32_e32 v57, v57
	v_rcp_f32_e32 v68, v68
	v_rcp_f32_e32 v69, v69
	v_pk_mul_f32 v[56:57], v[60:61], v[56:57] op_sel_hi:[0,1]
	v_pk_mul_f32 v[56:57], v[72:73], v[56:57]
	v_pk_mul_f32 v[62:63], v[60:61], v[68:69] op_sel_hi:[0,1]
	v_pk_mul_f32 v[62:63], v[46:47], v[62:63]
	v_pk_mul_f32 v[46:47], v[48:49], v[66:67] op_sel_hi:[1,0]
	s_nop 0
	v_exp_f32_e32 v46, v46
	v_exp_f32_e32 v47, v47
	s_nop 0
	v_pk_add_f32 v[46:47], v[46:47], 1.0 op_sel_hi:[1,0]
	s_nop 0
	v_rcp_f32_e32 v46, v46
	v_rcp_f32_e32 v47, v47
	s_nop 0
	v_pk_mul_f32 v[46:47], v[60:61], v[46:47] op_sel_hi:[0,1]
	v_pk_mul_f32 v[60:61], v[64:65], v[46:47]
	v_cvt_pk_bf16_f32 v46, v54, v55
	v_mul_f32_e32 v54, 0xbfb8aa3b, v163
	v_cvt_pk_bf16_f32 v47, v56, v57
	v_pk_mul_f32 v[56:57], v[38:39], v[54:55] op_sel_hi:[1,0]
	v_cvt_pk_bf16_f32 v48, v62, v63
	v_cvt_pk_bf16_f32 v49, v60, v61
	global_store_dwordx4 v[58:59], v[46:49], off
	v_exp_f32_e32 v56, v56
	v_exp_f32_e32 v57, v57
	v_mul_f32_e32 v48, v163, v163
	v_pk_mul_f32 v[38:39], v[38:39], v[50:51]
	v_pk_mul_f32 v[40:41], v[40:41], v[54:55] op_sel_hi:[1,0]
	v_pk_add_f32 v[56:57], v[56:57], 1.0 op_sel_hi:[1,0]
	v_exp_f32_e32 v40, v40
	v_rcp_f32_e32 v56, v56
	v_rcp_f32_e32 v57, v57
	v_exp_f32_e32 v41, v41
	v_add_u32_e32 v46, 0x90, v146
	v_mad_i64_i32 v[46:47], s[10:11], v46, s99, v[148:149]
	v_pk_mul_f32 v[50:51], v[48:49], v[56:57] op_sel_hi:[0,1]
	v_pk_mul_f32 v[38:39], v[38:39], v[50:51]
	v_pk_mul_f32 v[50:51], v[30:31], v[54:55] op_sel_hi:[1,0]
	v_pk_mul_f32 v[30:31], v[30:31], v[42:43]
	v_exp_f32_e32 v50, v50
	v_exp_f32_e32 v51, v51
	v_pk_add_f32 v[40:41], v[40:41], 1.0 op_sel_hi:[1,0]
	v_lshl_add_u64 v[46:47], v[46:47], 0, v[110:111]
	v_rcp_f32_e32 v40, v40
	v_pk_add_f32 v[50:51], v[50:51], 1.0 op_sel_hi:[1,0]
	v_rcp_f32_e32 v41, v41
	v_rcp_f32_e32 v50, v50
	v_rcp_f32_e32 v51, v51
	v_pk_mul_f32 v[40:41], v[48:49], v[40:41] op_sel_hi:[0,1]
	v_pk_mul_f32 v[40:41], v[52:53], v[40:41]
	v_pk_mul_f32 v[42:43], v[48:49], v[50:51] op_sel_hi:[0,1]
	v_pk_mul_f32 v[42:43], v[30:31], v[42:43]
	v_pk_mul_f32 v[30:31], v[32:33], v[54:55] op_sel_hi:[1,0]
	s_nop 0
	v_exp_f32_e32 v30, v30
	v_exp_f32_e32 v31, v31
	s_nop 0
	v_pk_add_f32 v[30:31], v[30:31], 1.0 op_sel_hi:[1,0]
	s_nop 0
	v_rcp_f32_e32 v30, v30
	v_rcp_f32_e32 v31, v31
	s_nop 0
	v_pk_mul_f32 v[30:31], v[48:49], v[30:31] op_sel_hi:[0,1]
	v_pk_mul_f32 v[44:45], v[44:45], v[30:31]
	v_cvt_pk_bf16_f32 v30, v38, v39
	v_mul_f32_e32 v38, 0xbfb8aa3b, v147
	v_cvt_pk_bf16_f32 v31, v40, v41
	v_pk_mul_f32 v[40:41], v[22:23], v[38:39] op_sel_hi:[1,0]
	v_cvt_pk_bf16_f32 v32, v42, v43
	v_cvt_pk_bf16_f32 v33, v44, v45
	global_store_dwordx4 v[46:47], v[30:33], off
	v_exp_f32_e32 v40, v40
	v_exp_f32_e32 v41, v41
	v_mul_f32_e32 v32, v147, v147
	v_pk_mul_f32 v[22:23], v[22:23], v[34:35]
	v_pk_mul_f32 v[24:25], v[24:25], v[38:39] op_sel_hi:[1,0]
	v_pk_add_f32 v[40:41], v[40:41], 1.0 op_sel_hi:[1,0]
	v_exp_f32_e32 v24, v24
	v_rcp_f32_e32 v40, v40
	v_rcp_f32_e32 v41, v41
	v_exp_f32_e32 v25, v25
	v_add_u32_e32 v30, 0xa0, v146
	v_mad_i64_i32 v[30:31], s[10:11], v30, s99, v[148:149]
	v_pk_mul_f32 v[34:35], v[32:33], v[40:41] op_sel_hi:[0,1]
	v_pk_mul_f32 v[22:23], v[22:23], v[34:35]
	v_pk_mul_f32 v[34:35], v[14:15], v[38:39] op_sel_hi:[1,0]
	v_pk_mul_f32 v[14:15], v[14:15], v[26:27]
	v_exp_f32_e32 v34, v34
	v_exp_f32_e32 v35, v35
	v_pk_add_f32 v[24:25], v[24:25], 1.0 op_sel_hi:[1,0]
	v_lshl_add_u64 v[30:31], v[30:31], 0, v[110:111]
	v_rcp_f32_e32 v24, v24
	v_pk_add_f32 v[34:35], v[34:35], 1.0 op_sel_hi:[1,0]
	v_rcp_f32_e32 v25, v25
	v_rcp_f32_e32 v34, v34
	v_rcp_f32_e32 v35, v35
	v_pk_mul_f32 v[24:25], v[32:33], v[24:25] op_sel_hi:[0,1]
	v_pk_mul_f32 v[24:25], v[36:37], v[24:25]
	v_pk_mul_f32 v[26:27], v[32:33], v[34:35] op_sel_hi:[0,1]
	v_pk_mul_f32 v[26:27], v[14:15], v[26:27]
	v_pk_mul_f32 v[14:15], v[16:17], v[38:39] op_sel_hi:[1,0]
	s_nop 0
	v_exp_f32_e32 v14, v14
	v_exp_f32_e32 v15, v15
	s_nop 0
	v_pk_add_f32 v[14:15], v[14:15], 1.0 op_sel_hi:[1,0]
	s_nop 0
	v_rcp_f32_e32 v14, v14
	v_rcp_f32_e32 v15, v15
	s_nop 0
	v_pk_mul_f32 v[14:15], v[32:33], v[14:15] op_sel_hi:[0,1]
	v_pk_mul_f32 v[28:29], v[28:29], v[14:15]
	v_cvt_pk_bf16_f32 v14, v22, v23
	v_cvt_pk_bf16_f32 v15, v24, v25
	v_cvt_pk_bf16_f32 v16, v26, v27
	s_nop 0
	v_cvt_pk_bf16_f32 v17, v28, v29
	global_store_dwordx4 v[30:31], v[14:17], off
	s_nop 1
	v_mul_f32_e32 v16, v0, v0
	v_mul_f32_e32 v0, 0xbfb8aa3b, v0
	v_pk_mul_f32 v[22:23], v[6:7], v[0:1] op_sel_hi:[1,0]
	v_pk_mul_f32 v[6:7], v[6:7], v[18:19]
	v_exp_f32_e32 v22, v22
	v_exp_f32_e32 v23, v23
	v_pk_mul_f32 v[8:9], v[8:9], v[0:1] op_sel_hi:[1,0]
	v_add_u32_e32 v14, 0xb0, v146
	v_exp_f32_e32 v8, v8
	v_pk_add_f32 v[22:23], v[22:23], 1.0 op_sel_hi:[1,0]
	v_exp_f32_e32 v9, v9
	v_rcp_f32_e32 v22, v22
	v_rcp_f32_e32 v23, v23
	v_mad_i64_i32 v[14:15], s[10:11], v14, s99, v[148:149]
	v_pk_add_f32 v[8:9], v[8:9], 1.0 op_sel_hi:[1,0]
	v_pk_mul_f32 v[18:19], v[16:17], v[22:23] op_sel_hi:[0,1]
	v_pk_mul_f32 v[6:7], v[6:7], v[18:19]
	v_pk_mul_f32 v[18:19], v[2:3], v[0:1] op_sel_hi:[1,0]
	v_pk_mul_f32 v[2:3], v[2:3], v[10:11]
	v_exp_f32_e32 v18, v18
	v_exp_f32_e32 v19, v19
	v_rcp_f32_e32 v8, v8
	v_rcp_f32_e32 v9, v9
	v_lshl_add_u64 v[14:15], v[14:15], 0, v[110:111]
	v_pk_add_f32 v[18:19], v[18:19], 1.0 op_sel_hi:[1,0]
	s_mov_b64 s[10:11], -1
	v_rcp_f32_e32 v18, v18
	v_rcp_f32_e32 v19, v19
	v_pk_mul_f32 v[8:9], v[16:17], v[8:9] op_sel_hi:[0,1]
	v_pk_mul_f32 v[8:9], v[20:21], v[8:9]
	v_pk_mul_f32 v[10:11], v[16:17], v[18:19] op_sel_hi:[0,1]
	v_pk_mul_f32 v[10:11], v[2:3], v[10:11]
	v_pk_mul_f32 v[2:3], v[4:5], v[0:1] op_sel_hi:[1,0]
	s_nop 0
	v_exp_f32_e32 v2, v2
	v_exp_f32_e32 v3, v3
	s_nop 0
	v_pk_add_f32 v[2:3], v[2:3], 1.0 op_sel_hi:[1,0]
	s_nop 0
	v_rcp_f32_e32 v2, v2
	v_rcp_f32_e32 v3, v3
	s_nop 0
	v_pk_mul_f32 v[2:3], v[16:17], v[2:3] op_sel_hi:[0,1]
	v_pk_mul_f32 v[12:13], v[12:13], v[2:3]
	v_cvt_pk_bf16_f32 v2, v6, v7
	v_cvt_pk_bf16_f32 v3, v8, v9
	v_cvt_pk_bf16_f32 v4, v10, v11
	s_nop 0
	v_cvt_pk_bf16_f32 v5, v12, v13
	global_store_dwordx4 v[14:15], v[2:5], off
	s_cbranch_vccnz .LBB0_138
	s_nop 0
	v_mov_b32_e32 v2, v1
	v_mov_b32_e32 v3, v1
	v_mov_b32_e32 v0, v1
	v_mov_b64_e32 v[12:13], v[2:3]
	v_mov_b64_e32 v[10:11], v[0:1]
	s_andn2_b64 vcc, exec, s[14:15]
	s_nop 0
	v_mfma_f32_16x16x32_bf16 v[118:121], v[10:13], v[10:13], 0
	s_nop 0
	v_mfma_f32_16x16x32_bf16 v[110:113], v[10:13], v[10:13], 0
	s_nop 0
	v_mfma_f32_16x16x32_bf16 v[102:105], v[10:13], v[10:13], 0
	s_nop 0
	v_mfma_f32_16x16x32_bf16 v[94:97], v[10:13], v[10:13], 0
	s_nop 0
	v_mfma_f32_16x16x32_bf16 v[86:89], v[10:13], v[10:13], 0
	s_nop 0
	v_mfma_f32_16x16x32_bf16 v[78:81], v[10:13], v[10:13], 0
	s_nop 0
	v_mfma_f32_16x16x32_bf16 v[66:69], v[10:13], v[10:13], 0
	s_nop 0
	v_mfma_f32_16x16x32_bf16 v[58:61], v[10:13], v[10:13], 0
	s_nop 0
	v_mfma_f32_16x16x32_bf16 v[126:129], v[10:13], v[10:13], 0
	s_nop 0
	v_mfma_f32_16x16x32_bf16 v[122:125], v[10:13], v[10:13], 0
	s_nop 0
	v_mfma_f32_16x16x32_bf16 v[114:117], v[10:13], v[10:13], 0
	s_nop 0
	v_mfma_f32_16x16x32_bf16 v[106:109], v[10:13], v[10:13], 0
	s_nop 0
	v_mfma_f32_16x16x32_bf16 v[98:101], v[10:13], v[10:13], 0
	s_nop 0
	v_mfma_f32_16x16x32_bf16 v[90:93], v[10:13], v[10:13], 0
	s_nop 0
	v_mfma_f32_16x16x32_bf16 v[82:85], v[10:13], v[10:13], 0
	s_nop 0
	v_mfma_f32_16x16x32_bf16 v[74:77], v[10:13], v[10:13], 0
	s_nop 0
	v_mfma_f32_16x16x32_bf16 v[54:57], v[10:13], v[10:13], 0
	s_nop 0
	v_mfma_f32_16x16x32_bf16 v[46:49], v[10:13], v[10:13], 0
	s_nop 0
	v_mfma_f32_16x16x32_bf16 v[38:41], v[10:13], v[10:13], 0
	s_nop 0
	v_mfma_f32_16x16x32_bf16 v[30:33], v[10:13], v[10:13], 0
	s_nop 0
	v_mfma_f32_16x16x32_bf16 v[22:25], v[10:13], v[10:13], 0
	s_nop 0
	v_mfma_f32_16x16x32_bf16 v[14:17], v[10:13], v[10:13], 0
	s_nop 0
	v_mfma_f32_16x16x32_bf16 v[6:9], v[10:13], v[10:13], 0
	s_nop 0
	v_mfma_f32_16x16x32_bf16 v[2:5], v[10:13], v[10:13], 0
	s_nop 0
	v_mfma_f32_16x16x32_bf16 v[70:73], v[10:13], v[10:13], 0
	s_nop 0
	v_mfma_f32_16x16x32_bf16 v[62:65], v[10:13], v[10:13], 0
	s_nop 0
	v_mfma_f32_16x16x32_bf16 v[50:53], v[10:13], v[10:13], 0
	s_nop 0
	v_mfma_f32_16x16x32_bf16 v[42:45], v[10:13], v[10:13], 0
	s_nop 0
	v_mfma_f32_16x16x32_bf16 v[34:37], v[10:13], v[10:13], 0
	s_nop 0
	v_mfma_f32_16x16x32_bf16 v[26:29], v[10:13], v[10:13], 0
	s_nop 0
	v_mfma_f32_16x16x32_bf16 v[18:21], v[10:13], v[10:13], 0
	s_nop 0
	v_mfma_f32_16x16x32_bf16 v[10:13], v[10:13], v[10:13], 0
	s_cbranch_vccnz .LBB0_137
	s_branch .LBB0_137
